# barrier poll loops without s_sleep
# speedup vs baseline: 1.0024x; 1.0024x over previous
.LBB0_14:
	s_nop 0
	global_load_dword v2, v0, s[6:7] offset:32 sc1
	s_waitcnt vmcnt(0)
	v_and_b32_e32 v2, 0xffff0000, v2
	v_cmp_ne_u32_e32 vcc, v2, v1
	s_or_b64 s[8:9], vcc, s[8:9]
	s_andn2_b64 exec, exec, s[8:9]
	s_cbranch_execnz .LBB0_14

.LBB0_125:
	global_load_dword v15, v16, s[6:7] sc1
	s_waitcnt lgkmcnt(0)
	global_load_dword v0, v16, s[8:9] sc1
	global_load_dword v1, v16, s[10:11] sc1
	global_load_dword v2, v16, s[12:13] sc1
	global_load_dword v3, v16, s[14:15] sc1
	global_load_dword v4, v16, s[16:17] sc1
	global_load_dword v5, v16, s[18:19] sc1
	global_load_dword v6, v16, s[20:21] sc1
	global_load_dword v7, v16, s[22:23] sc1
	global_load_dword v8, v16, s[28:29] sc1
	global_load_dword v9, v16, s[30:31] sc1
	global_load_dword v10, v16, s[34:35] sc1
	global_load_dword v11, v16, s[38:39] sc1
	global_load_dword v12, v16, s[40:41] sc1
	global_load_dword v13, v16, s[42:43] sc1
	global_load_dword v14, v16, s[44:45] sc1
	s_mov_b64 s[46:47], -1
	s_mov_b64 s[48:49], -1
	s_waitcnt vmcnt(14)
	v_add_u32_e32 v17, v0, v15
	s_waitcnt vmcnt(13)
	v_add_u32_e32 v17, v17, v1
	s_waitcnt vmcnt(12)
	v_add_u32_e32 v17, v17, v2
	s_waitcnt vmcnt(11)
	v_add_u32_e32 v17, v17, v3
	s_waitcnt vmcnt(10)
	v_add_u32_e32 v17, v17, v4
	s_waitcnt vmcnt(9)
	v_add_u32_e32 v17, v17, v5
	s_waitcnt vmcnt(8)
	v_add_u32_e32 v17, v17, v6
	s_waitcnt vmcnt(7)
	v_add_u32_e32 v17, v17, v7
	s_waitcnt vmcnt(6)
	v_add_u32_e32 v17, v17, v8
	s_waitcnt vmcnt(5)
	v_add_u32_e32 v17, v17, v9
	s_waitcnt vmcnt(4)
	v_add_u32_e32 v17, v17, v10
	s_waitcnt vmcnt(3)
	v_add_u32_e32 v17, v17, v11
	s_waitcnt vmcnt(2)
	v_add_u32_e32 v17, v17, v12
	s_waitcnt vmcnt(1)
	v_add_u32_e32 v17, v17, v13
	s_waitcnt vmcnt(0)
	v_add_u32_e32 v17, v17, v14
	v_cmp_eq_u32_e32 vcc, s33, v17
	s_cbranch_vccnz .LBB0_124
	s_and_b32 s46, s37, 0xff
	s_cmp_eq_u32 s46, 0
	s_mov_b64 s[46:47], -1
	s_mov_b64 s[50:51], -1
	s_nop 0
	s_cbranch_scc0 .LBB0_129
	global_load_dword v17, v16, s[4:5] sc1
	s_waitcnt vmcnt(0)
	v_cmp_eq_u32_e32 vcc, 0, v17
	s_cbranch_vccnz .LBB0_131
	s_mov_b64 s[50:51], 0

.LBB0_144:
	s_and_b32 s20, s3, 0xff
	s_mov_b64 s[18:19], -1
	s_cmp_lg_u32 s20, 0
	s_mov_b64 s[22:23], -1
	s_nop 0
	s_cbranch_scc1 .LBB0_147
	global_load_dword v2, v0, s[10:11] sc1
	s_waitcnt vmcnt(0)
	v_cmp_eq_u32_e32 vcc, 0, v2
	s_cbranch_vccnz .LBB0_149
	s_mov_b64 s[22:23], 0
	s_mov_b64 s[20:21], -1

.LBB0_161:
	s_and_b32 s18, s3, 0xff
	s_cmp_lg_u32 s18, 0
	s_mov_b64 s[20:21], -1
	s_nop 0
	s_cbranch_scc1 .LBB0_164
	global_load_dword v1, v0, s[10:11] sc1
	s_waitcnt vmcnt(0)
	v_cmp_eq_u32_e32 vcc, 0, v1
	s_cbranch_vccnz .LBB0_166
	s_mov_b64 s[20:21], 0
	s_mov_b64 s[18:19], -1

.LBB0_925:
	v_readlane_b32 s12, v251, 43
	v_readlane_b32 s13, v251, 44
	global_load_dword v1, v33, s[84:85] sc1
	s_waitcnt lgkmcnt(0)
	global_load_dword v0, v33, s[88:89] sc1
	s_mov_b64 s[14:15], -1
	s_waitcnt vmcnt(0)
	v_add_u32_e32 v16, v0, v1
	global_load_dword v2, v33, s[12:13] sc1
	v_readlane_b32 s12, v251, 45
	v_readlane_b32 s13, v251, 46
	s_waitcnt vmcnt(0)
	v_add_u32_e32 v16, v16, v2
	s_nop 2
	global_load_dword v3, v33, s[12:13] sc1
	v_readlane_b32 s12, v251, 47
	v_readlane_b32 s13, v251, 48
	s_waitcnt vmcnt(0)
	v_add_u32_e32 v16, v16, v3
	s_nop 2
	global_load_dword v4, v33, s[12:13] sc1
	v_readlane_b32 s12, v251, 49
	v_readlane_b32 s13, v251, 50
	s_waitcnt vmcnt(0)
	v_add_u32_e32 v16, v16, v4
	s_nop 2
	global_load_dword v5, v33, s[12:13] sc1
	v_readlane_b32 s12, v251, 51
	v_readlane_b32 s13, v251, 52
	s_waitcnt vmcnt(0)
	v_add_u32_e32 v16, v16, v5
	s_nop 2
	global_load_dword v6, v33, s[12:13] sc1
	v_readlane_b32 s12, v251, 53
	v_readlane_b32 s13, v251, 54
	s_waitcnt vmcnt(0)
	v_add_u32_e32 v16, v16, v6
	s_nop 2
	global_load_dword v7, v33, s[12:13] sc1
	v_readlane_b32 s12, v251, 55
	v_readlane_b32 s13, v251, 56
	s_waitcnt vmcnt(0)
	v_add_u32_e32 v16, v16, v7
	s_nop 2
	global_load_dword v8, v33, s[12:13] sc1
	v_readlane_b32 s12, v251, 57
	v_readlane_b32 s13, v251, 58
	s_waitcnt vmcnt(0)
	v_add_u32_e32 v16, v16, v8
	s_nop 2
	global_load_dword v9, v33, s[12:13] sc1
	v_readlane_b32 s12, v251, 59
	v_readlane_b32 s13, v251, 60
	s_waitcnt vmcnt(0)
	v_add_u32_e32 v16, v16, v9
	s_nop 2
	global_load_dword v10, v33, s[12:13] sc1
	v_readlane_b32 s12, v251, 61
	v_readlane_b32 s13, v251, 62
	s_waitcnt vmcnt(0)
	v_add_u32_e32 v16, v16, v10
	s_nop 2
	global_load_dword v11, v33, s[12:13] sc1
	v_readlane_b32 s12, v251, 63
	v_readlane_b32 s13, v252, 0
	s_waitcnt vmcnt(0)
	v_add_u32_e32 v16, v16, v11
	s_nop 2
	global_load_dword v12, v33, s[12:13] sc1
	v_readlane_b32 s12, v252, 1
	v_readlane_b32 s13, v252, 2
	s_waitcnt vmcnt(0)
	v_add_u32_e32 v16, v16, v12
	s_nop 2
	global_load_dword v13, v33, s[12:13] sc1
	v_readlane_b32 s12, v252, 3
	v_readlane_b32 s13, v252, 4
	s_waitcnt vmcnt(0)
	v_add_u32_e32 v16, v16, v13
	s_nop 2
	global_load_dword v14, v33, s[12:13] sc1
	v_readlane_b32 s12, v252, 5
	v_readlane_b32 s13, v252, 6
	s_waitcnt vmcnt(0)
	v_add_u32_e32 v16, v16, v14
	s_nop 2
	global_load_dword v15, v33, s[12:13] sc1
	s_mov_b64 s[12:13], -1
	s_waitcnt vmcnt(0)
	v_add_u32_e32 v16, v16, v15
	v_cmp_eq_u32_e32 vcc, s83, v16
	s_cbranch_vccnz .LBB0_924
	s_and_b32 s9, s8, 0xff
	s_cmp_eq_u32 s9, 0
	s_mov_b64 s[16:17], -1
	s_nop 0
	s_cbranch_scc0 .LBB0_929
	global_load_dword v16, v33, s[86:87] sc1
	s_waitcnt vmcnt(0)
	v_cmp_eq_u32_e32 vcc, 0, v16
	s_cbranch_vccnz .LBB0_931
	s_mov_b64 s[16:17], 0

.LBB0_943:
	s_and_b32 s8, s2, 0xff
	s_mov_b64 s[34:35], -1
	s_cmp_lg_u32 s8, 0
	s_mov_b64 s[66:67], -1
	s_nop 0
	s_cbranch_scc1 .LBB0_946
	global_load_dword v0, v33, s[86:87] sc1
	s_waitcnt vmcnt(0)
	v_cmp_eq_u32_e32 vcc, 0, v0
	s_cbranch_vccnz .LBB0_948
	s_mov_b64 s[66:67], 0
	s_mov_b64 s[44:45], -1

.LBB0_960:
	s_and_b32 s8, s2, 0xff
	s_mov_b64 s[30:31], -1
	s_cmp_lg_u32 s8, 0
	s_mov_b64 s[44:45], -1
	s_nop 0
	s_cbranch_scc1 .LBB0_963
	global_load_dword v0, v33, s[86:87] sc1
	s_waitcnt vmcnt(0)
	v_cmp_eq_u32_e32 vcc, 0, v0
	s_cbranch_vccnz .LBB0_965
	s_mov_b64 s[44:45], 0
	s_mov_b64 s[34:35], -1

.LBB0_1579:
	v_readlane_b32 s14, v251, 43
	v_readlane_b32 s15, v251, 44
	global_load_dword v1, v33, s[84:85] sc1
	s_waitcnt lgkmcnt(0)
	global_load_dword v0, v33, s[88:89] sc1
	s_mov_b64 s[16:17], -1
	s_waitcnt vmcnt(0)
	v_add_u32_e32 v16, v0, v1
	global_load_dword v2, v33, s[14:15] sc1
	v_readlane_b32 s14, v251, 45
	v_readlane_b32 s15, v251, 46
	s_waitcnt vmcnt(0)
	v_add_u32_e32 v16, v16, v2
	s_nop 2
	global_load_dword v3, v33, s[14:15] sc1
	v_readlane_b32 s14, v251, 47
	v_readlane_b32 s15, v251, 48
	s_waitcnt vmcnt(0)
	v_add_u32_e32 v16, v16, v3
	s_nop 2
	global_load_dword v4, v33, s[14:15] sc1
	v_readlane_b32 s14, v251, 49
	v_readlane_b32 s15, v251, 50
	s_waitcnt vmcnt(0)
	v_add_u32_e32 v16, v16, v4
	s_nop 2
	global_load_dword v5, v33, s[14:15] sc1
	v_readlane_b32 s14, v251, 51
	v_readlane_b32 s15, v251, 52
	s_waitcnt vmcnt(0)
	v_add_u32_e32 v16, v16, v5
	s_nop 2
	global_load_dword v6, v33, s[14:15] sc1
	v_readlane_b32 s14, v251, 53
	v_readlane_b32 s15, v251, 54
	s_waitcnt vmcnt(0)
	v_add_u32_e32 v16, v16, v6
	s_nop 2
	global_load_dword v7, v33, s[14:15] sc1
	v_readlane_b32 s14, v251, 55
	v_readlane_b32 s15, v251, 56
	s_waitcnt vmcnt(0)
	v_add_u32_e32 v16, v16, v7
	s_nop 2
	global_load_dword v8, v33, s[14:15] sc1
	v_readlane_b32 s14, v251, 57
	v_readlane_b32 s15, v251, 58
	s_waitcnt vmcnt(0)
	v_add_u32_e32 v16, v16, v8
	s_nop 2
	global_load_dword v9, v33, s[14:15] sc1
	v_readlane_b32 s14, v251, 59
	v_readlane_b32 s15, v251, 60
	s_waitcnt vmcnt(0)
	v_add_u32_e32 v16, v16, v9
	s_nop 2
	global_load_dword v10, v33, s[14:15] sc1
	v_readlane_b32 s14, v251, 61
	v_readlane_b32 s15, v251, 62
	s_waitcnt vmcnt(0)
	v_add_u32_e32 v16, v16, v10
	s_nop 2
	global_load_dword v11, v33, s[14:15] sc1
	v_readlane_b32 s14, v251, 63
	v_readlane_b32 s15, v252, 0
	s_waitcnt vmcnt(0)
	v_add_u32_e32 v16, v16, v11
	s_nop 2
	global_load_dword v12, v33, s[14:15] sc1
	v_readlane_b32 s14, v252, 1
	v_readlane_b32 s15, v252, 2
	s_waitcnt vmcnt(0)
	v_add_u32_e32 v16, v16, v12
	s_nop 2
	global_load_dword v13, v33, s[14:15] sc1
	v_readlane_b32 s14, v252, 3
	v_readlane_b32 s15, v252, 4
	s_waitcnt vmcnt(0)
	v_add_u32_e32 v16, v16, v13
	s_nop 2
	global_load_dword v14, v33, s[14:15] sc1
	v_readlane_b32 s14, v252, 5
	v_readlane_b32 s15, v252, 6
	s_waitcnt vmcnt(0)
	v_add_u32_e32 v16, v16, v14
	s_nop 2
	global_load_dword v15, v33, s[14:15] sc1
	s_mov_b64 s[14:15], -1
	s_waitcnt vmcnt(0)
	v_add_u32_e32 v16, v16, v15
	v_cmp_eq_u32_e32 vcc, s83, v16
	s_cbranch_vccnz .LBB0_1578
	s_and_b32 s9, s8, 0xff
	s_cmp_eq_u32 s9, 0
	s_mov_b64 s[18:19], -1
	s_nop 0
	s_cbranch_scc0 .LBB0_1583
	global_load_dword v16, v33, s[86:87] sc1
	s_waitcnt vmcnt(0)
	v_cmp_eq_u32_e32 vcc, 0, v16
	s_cbranch_vccnz .LBB0_1585
	s_mov_b64 s[18:19], 0

.LBB0_1597:
	s_and_b32 s8, s2, 0xff
	s_mov_b64 s[44:45], -1
	s_cmp_lg_u32 s8, 0
	s_mov_b64 s[72:73], -1
	s_nop 0
	s_cbranch_scc1 .LBB0_1600
	global_load_dword v0, v33, s[86:87] sc1
	s_waitcnt vmcnt(0)
	v_cmp_eq_u32_e32 vcc, 0, v0
	s_cbranch_vccnz .LBB0_1602
	s_mov_b64 s[72:73], 0
	s_mov_b64 s[66:67], -1

.LBB0_1699:
	v_readlane_b32 s12, v251, 43
	v_readlane_b32 s13, v251, 44
	global_load_dword v1, v33, s[84:85] sc1
	s_waitcnt lgkmcnt(0)
	global_load_dword v0, v33, s[88:89] sc1
	s_mov_b64 s[14:15], -1
	s_waitcnt vmcnt(0)
	v_add_u32_e32 v16, v0, v1
	global_load_dword v2, v33, s[12:13] sc1
	v_readlane_b32 s12, v251, 45
	v_readlane_b32 s13, v251, 46
	s_waitcnt vmcnt(0)
	v_add_u32_e32 v16, v16, v2
	s_nop 2
	global_load_dword v3, v33, s[12:13] sc1
	v_readlane_b32 s12, v251, 47
	v_readlane_b32 s13, v251, 48
	s_waitcnt vmcnt(0)
	v_add_u32_e32 v16, v16, v3
	s_nop 2
	global_load_dword v4, v33, s[12:13] sc1
	v_readlane_b32 s12, v251, 49
	v_readlane_b32 s13, v251, 50
	s_waitcnt vmcnt(0)
	v_add_u32_e32 v16, v16, v4
	s_nop 2
	global_load_dword v5, v33, s[12:13] sc1
	v_readlane_b32 s12, v251, 51
	v_readlane_b32 s13, v251, 52
	s_waitcnt vmcnt(0)
	v_add_u32_e32 v16, v16, v5
	s_nop 2
	global_load_dword v6, v33, s[12:13] sc1
	v_readlane_b32 s12, v251, 53
	v_readlane_b32 s13, v251, 54
	s_waitcnt vmcnt(0)
	v_add_u32_e32 v16, v16, v6
	s_nop 2
	global_load_dword v7, v33, s[12:13] sc1
	v_readlane_b32 s12, v251, 55
	v_readlane_b32 s13, v251, 56
	s_waitcnt vmcnt(0)
	v_add_u32_e32 v16, v16, v7
	s_nop 2
	global_load_dword v8, v33, s[12:13] sc1
	v_readlane_b32 s12, v251, 57
	v_readlane_b32 s13, v251, 58
	s_waitcnt vmcnt(0)
	v_add_u32_e32 v16, v16, v8
	s_nop 2
	global_load_dword v9, v33, s[12:13] sc1
	v_readlane_b32 s12, v251, 59
	v_readlane_b32 s13, v251, 60
	s_waitcnt vmcnt(0)
	v_add_u32_e32 v16, v16, v9
	s_nop 2
	global_load_dword v10, v33, s[12:13] sc1
	v_readlane_b32 s12, v251, 61
	v_readlane_b32 s13, v251, 62
	s_waitcnt vmcnt(0)
	v_add_u32_e32 v16, v16, v10
	s_nop 2
	global_load_dword v11, v33, s[12:13] sc1
	v_readlane_b32 s12, v251, 63
	v_readlane_b32 s13, v252, 0
	s_waitcnt vmcnt(0)
	v_add_u32_e32 v16, v16, v11
	s_nop 2
	global_load_dword v12, v33, s[12:13] sc1
	v_readlane_b32 s12, v252, 1
	v_readlane_b32 s13, v252, 2
	s_waitcnt vmcnt(0)
	v_add_u32_e32 v16, v16, v12
	s_nop 2
	global_load_dword v13, v33, s[12:13] sc1
	v_readlane_b32 s12, v252, 3
	v_readlane_b32 s13, v252, 4
	s_waitcnt vmcnt(0)
	v_add_u32_e32 v16, v16, v13
	s_nop 2
	global_load_dword v14, v33, s[12:13] sc1
	v_readlane_b32 s12, v252, 5
	v_readlane_b32 s13, v252, 6
	s_waitcnt vmcnt(0)
	v_add_u32_e32 v16, v16, v14
	s_nop 2
	global_load_dword v15, v33, s[12:13] sc1
	s_mov_b64 s[12:13], -1
	s_waitcnt vmcnt(0)
	v_add_u32_e32 v16, v16, v15
	v_cmp_eq_u32_e32 vcc, s83, v16
	s_cbranch_vccnz .LBB0_1698
	s_and_b32 s12, s9, 0xff
	s_cmp_eq_u32 s12, 0
	s_mov_b64 s[12:13], -1
	s_mov_b64 s[16:17], -1
	s_nop 0
	s_cbranch_scc0 .LBB0_1703
	global_load_dword v16, v33, s[86:87] sc1
	s_waitcnt vmcnt(0)
	v_cmp_eq_u32_e32 vcc, 0, v16
	s_cbranch_vccnz .LBB0_1705
	s_mov_b64 s[16:17], 0

.LBB0_1717:
	s_and_b32 s9, s8, 0xff
	s_mov_b64 s[34:35], -1
	s_cmp_lg_u32 s9, 0
	s_mov_b64 s[66:67], -1
	s_nop 0
	s_cbranch_scc1 .LBB0_1720
	global_load_dword v0, v33, s[86:87] sc1
	s_waitcnt vmcnt(0)
	v_cmp_eq_u32_e32 vcc, 0, v0
	s_cbranch_vccnz .LBB0_1722
	s_mov_b64 s[66:67], 0
	s_mov_b64 s[44:45], -1

.LBB0_1734:
	s_and_b32 s9, s8, 0xff
	s_mov_b64 s[30:31], -1
	s_cmp_lg_u32 s9, 0
	s_mov_b64 s[44:45], -1
	s_nop 0
	s_cbranch_scc1 .LBB0_1737
	global_load_dword v0, v33, s[86:87] sc1
	s_waitcnt vmcnt(0)
	v_cmp_eq_u32_e32 vcc, 0, v0
	s_cbranch_vccnz .LBB0_1739
	s_mov_b64 s[44:45], 0
	s_mov_b64 s[34:35], -1
